# phase-2 item table re-balanced with model 0.55*nj+0.67*NS+16
# baseline (speedup 1.0000x reference)
_ZL7idx_tab:
	.short	212
	.short	210
	.short	13
	.short	196
	.short	65
	.short	340
	.short	466
	.short	397
	.short	452
	.short	321
	.short	660
	.short	658
	.short	653
	.short	580
	.short	704
	.short	916
	.short	850
	.short	973
	.short	772
	.short	770
	.short	1236
	.short	1234
	.short	1101
	.short	1156
	.short	1025
	.short	1300
	.short	1426
	.short	1421
	.short	1476
	.short	1282
	.short	1748
	.short	1682
	.short	1549
	.short	1668
	.short	1729
	.short	2004
	.short	1810
	.short	1805
	.short	1924
	.short	1985
	.short	20
	.short	82
	.short	141
	.short	68
	.short	193
	.short	468
	.short	402
	.short	333
	.short	388
	.short	387
	.short	724
	.short	722
	.short	525
	.short	644
	.short	513
	.short	980
	.short	914
	.short	845
	.short	900
	.short	834
	.short	1044
	.short	1106
	.short	1229
	.short	1092
	.short	1153
	.short	1364
	.short	1362
	.short	1293
	.short	1348
	.short	1344
	.short	1556
	.short	1618
	.short	1677
	.short	1540
	.short	1667
	.short	1876
	.short	2002
	.short	1997
	.short	1796
	.short	1857
	.short	23
	.short	211
	.short	12
	.short	69
	.short	195
	.short	343
	.short	403
	.short	332
	.short	261
	.short	258
	.short	663
	.short	595
	.short	716
	.short	517
	.short	707
	.short	919
	.short	915
	.short	844
	.short	901
	.short	771
	.short	1111
	.short	1171
	.short	1036
	.short	1029
	.short	1155
	.short	1367
	.short	1299
	.short	1356
	.short	1285
	.short	1283
	.short	1751
	.short	1555
	.short	1676
	.short	1669
	.short	1731
	.short	2007
	.short	1875
	.short	1868
	.short	1861
	.short	1923
	.short	215
	.short	19
	.short	76
	.short	5
	.short	2
	.short	407
	.short	275
	.short	396
	.short	389
	.short	323
	.short	727
	.short	531
	.short	524
	.short	645
	.short	578
	.short	791
	.short	787
	.short	908
	.short	965
	.short	835
	.short	1047
	.short	1235
	.short	1164
	.short	1221
	.short	1026
	.short	1495
	.short	1491
	.short	1420
	.short	1413
	.short	1409
	.short	1687
	.short	1747
	.short	1740
	.short	1733
	.short	1538
	.short	1879
	.short	2003
	.short	1996
	.short	1989
	.short	1987
	.short	31
	.short	204
	.short	11
	.short	132
	.short	128
	.short	351
	.short	268
	.short	459
	.short	324
	.short	257
	.short	671
	.short	652
	.short	523
	.short	708
	.short	576
	.short	863
	.short	972
	.short	779
	.short	836
	.short	960
	.short	1119
	.short	1100
	.short	1035
	.short	1028
	.short	1091
	.short	1311
	.short	1292
	.short	1355
	.short	1284
	.short	1280
	.short	1567
	.short	1612
	.short	1547
	.short	1604
	.short	1600
	.short	1887
	.short	1804
	.short	1931
	.short	1988
	.short	1792
	.short	223
	.short	140
	.short	75
	.short	4
	.short	192
	.short	479
	.short	460
	.short	267
	.short	260
	.short	385
	.short	543
	.short	588
	.short	587
	.short	516
	.short	579
	.short	927
	.short	780
	.short	971
	.short	964
	.short	833
	.short	1183
	.short	1228
	.short	1163
	.short	1220
	.short	1024
	.short	1439
	.short	1484
	.short	1483
	.short	1412
	.short	1408
	.short	1631
	.short	1548
	.short	1611
	.short	1732
	.short	1728
	.short	1951
	.short	1932
	.short	1867
	.short	1860
	.short	1920
	.short	84
	.short	146
	.short	207
	.short	6
	.short	65535
	.short	404
	.short	338
	.short	463
	.short	390
	.short	65535
	.short	596
	.short	530
	.short	591
	.short	646
	.short	65535
	.short	852
	.short	978
	.short	783
	.short	774
	.short	65535
	.short	1172
	.short	1042
	.short	1039
	.short	1030
	.short	65535
	.short	1428
	.short	1490
	.short	1359
	.short	1350
	.short	65535
	.short	1684
	.short	1746
	.short	1743
	.short	1606
	.short	65535
	.short	1812
	.short	1874
	.short	1871
	.short	1798
	.short	65535
	.short	148
	.short	18
	.short	79
	.short	134
	.short	65535
	.short	276
	.short	274
	.short	335
	.short	262
	.short	65535
	.short	532
	.short	594
	.short	655
	.short	710
	.short	65535
	.short	788
	.short	786
	.short	847
	.short	838
	.short	65535
	.short	1108
	.short	1170
	.short	1167
	.short	1158
	.short	65535
	.short	1492
	.short	1298
	.short	1423
	.short	1414
	.short	65535
	.short	1620
	.short	1554
	.short	1679
	.short	1670
	.short	65535
	.short	1940
	.short	1938
	.short	1935
	.short	1926
	.short	65535
	.short	91
	.short	154
	.short	80
	.short	65535
	.short	65535
	.short	347
	.short	474
	.short	400
	.short	65535
	.short	65535
	.short	667
	.short	538
	.short	656
	.short	65535
	.short	65535
	.short	795
	.short	794
	.short	848
	.short	65535
	.short	65535
	.short	1179
	.short	1050
	.short	1040
	.short	65535
	.short	65535
	.short	1499
	.short	1434
	.short	1360
	.short	65535
	.short	65535
	.short	1563
	.short	1690
	.short	1616
	.short	65535
	.short	65535
	.short	1819
	.short	1882
	.short	1872
	.short	65535
	.short	65535
	.short	219
	.short	90
	.short	208
	.short	65535
	.short	65535
	.short	411
	.short	410
	.short	336
	.short	65535
	.short	65535
	.short	603
	.short	730
	.short	592
	.short	65535
	.short	65535
	.short	987
	.short	922
	.short	912
	.short	65535
	.short	65535
	.short	1051
	.short	1114
	.short	1168
	.short	65535
	.short	65535
	.short	1371
	.short	1306
	.short	1488
	.short	65535
	.short	65535
	.short	1627
	.short	1626
	.short	1552
	.short	65535
	.short	65535
	.short	2011
	.short	2010
	.short	1808
	.short	65535
	.short	65535
	.short	28
	.short	152
	.short	81
	.short	65535
	.short	65535
	.short	284
	.short	344
	.short	401
	.short	65535
	.short	65535
	.short	540
	.short	600
	.short	721
	.short	65535
	.short	65535
	.short	988
	.short	792
	.short	977
	.short	65535
	.short	65535
	.short	1244
	.short	1112
	.short	1041
	.short	65535
	.short	65535
	.short	1500
	.short	1368
	.short	1425
	.short	65535
	.short	65535
	.short	1564
	.short	1624
	.short	1745
	.short	65535
	.short	65535
	.short	1948
	.short	1816
	.short	1937
	.short	65535
	.short	65535
	.short	92
	.short	88
	.short	145
	.short	65535
	.short	65535
	.short	412
	.short	280
	.short	273
	.short	65535
	.short	65535
	.short	668
	.short	664
	.short	593
	.short	65535
	.short	65535
	.short	796
	.short	920
	.short	785
	.short	65535
	.short	65535
	.short	1052
	.short	1048
	.short	1233
	.short	65535
	.short	65535
	.short	1308
	.short	1432
	.short	1361
	.short	65535
	.short	65535
	.short	1628
	.short	1688
	.short	1617
	.short	65535
	.short	65535
	.short	1884
	.short	1880
	.short	2001
	.short	65535
	.short	65535
	.short	158
	.short	93
	.short	143
	.short	194
	.short	65535
	.short	414
	.short	477
	.short	399
	.short	448
	.short	65535
	.short	670
	.short	541
	.short	527
	.short	641
	.short	65535
	.short	990
	.short	925
	.short	911
	.short	897
	.short	65535
	.short	1246
	.short	1245
	.short	1103
	.short	1089
	.short	65535
	.short	1438
	.short	1309
	.short	1487
	.short	1281
	.short	65535
	.short	1758
	.short	1757
	.short	1615
	.short	1602
	.short	65535
	.short	1822
	.short	1885
	.short	1999
	.short	1921
	.short	65535
	.short	222
	.short	29
	.short	15
	.short	64
	.short	65535
	.short	478
	.short	413
	.short	271
	.short	386
	.short	65535
	.short	542
	.short	733
	.short	719
	.short	512
	.short	65535
	.short	926
	.short	797
	.short	975
	.short	768
	.short	65535
	.short	1118
	.short	1053
	.short	1231
	.short	1217
	.short	65535
	.short	1502
	.short	1437
	.short	1295
	.short	1475
	.short	65535
	.short	1630
	.short	1693
	.short	1551
	.short	1539
	.short	65535
	.short	1886
	.short	1821
	.short	1807
	.short	1793
	.short	65535
	.short	27
	.short	25
	.short	144
	.short	65535
	.short	65535
	.short	283
	.short	281
	.short	464
	.short	65535
	.short	65535
	.short	731
	.short	665
	.short	528
	.short	65535
	.short	65535
	.short	923
	.short	857
	.short	784
	.short	65535
	.short	65535
	.short	1243
	.short	1241
	.short	1104
	.short	65535
	.short	65535
	.short	1307
	.short	1305
	.short	1424
	.short	65535
	.short	65535
	.short	1691
	.short	1753
	.short	1744
	.short	65535
	.short	65535
	.short	1883
	.short	1945
	.short	1936
	.short	65535
	.short	65535
	.short	155
	.short	89
	.short	16
	.short	65535
	.short	65535
	.short	475
	.short	473
	.short	272
	.short	65535
	.short	65535
	.short	539
	.short	729
	.short	720
	.short	65535
	.short	65535
	.short	859
	.short	985
	.short	976
	.short	65535
	.short	65535
	.short	1115
	.short	1177
	.short	1232
	.short	65535
	.short	65535
	.short	1435
	.short	1433
	.short	1296
	.short	65535
	.short	65535
	.short	1755
	.short	1689
	.short	1680
	.short	65535
	.short	65535
	.short	1947
	.short	1817
	.short	2000
	.short	65535
	.short	65535
	.short	214
	.short	149
	.short	202
	.short	70
	.short	65535
	.short	278
	.short	277
	.short	458
	.short	326
	.short	65535
	.short	726
	.short	597
	.short	650
	.short	518
	.short	65535
	.short	918
	.short	917
	.short	778
	.short	966
	.short	65535
	.short	1046
	.short	1237
	.short	1162
	.short	1222
	.short	65535
	.short	1366
	.short	1429
	.short	1290
	.short	1478
	.short	65535
	.short	1750
	.short	1557
	.short	1674
	.short	1734
	.short	65535
	.short	1878
	.short	1877
	.short	1866
	.short	1862
	.short	65535
	.short	22
	.short	213
	.short	138
	.short	198
	.short	65535
	.short	406
	.short	341
	.short	330
	.short	454
	.short	65535
	.short	662
	.short	533
	.short	714
	.short	582
	.short	65535
	.short	982
	.short	981
	.short	842
	.short	902
	.short	65535
	.short	1174
	.short	1109
	.short	1034
	.short	1094
	.short	65535
	.short	1430
	.short	1301
	.short	1482
	.short	1286
	.short	65535
	.short	1558
	.short	1749
	.short	1738
	.short	1542
	.short	65535
	.short	1942
	.short	1941
	.short	1994
	.short	1990
	.short	65535
	.short	95
	.short	94
	.short	142
	.short	66
	.short	1
	.short	287
	.short	286
	.short	398
	.short	256
	.short	449
	.short	735
	.short	606
	.short	526
	.short	642
	.short	514
	.short	799
	.short	798
	.short	846
	.short	769
	.short	961
	.short	1247
	.short	1182
	.short	1038
	.short	1027
	.short	1152
	.short	1503
	.short	1374
	.short	1358
	.short	1347
	.short	1345
	.short	1695
	.short	1566
	.short	1678
	.short	1536
	.short	1665
	.short	2015
	.short	1950
	.short	1934
	.short	1858
	.short	1856
	.short	159
	.short	30
	.short	78
	.short	67
	.short	129
	.short	415
	.short	350
	.short	334
	.short	384
	.short	320
	.short	607
	.short	734
	.short	590
	.short	515
	.short	640
	.short	991
	.short	862
	.short	974
	.short	896
	.short	832
	.short	1055
	.short	1054
	.short	1230
	.short	1088
	.short	1216
	.short	1375
	.short	1310
	.short	1294
	.short	1474
	.short	1473
	.short	1759
	.short	1694
	.short	1550
	.short	1664
	.short	1601
	.short	1823
	.short	2014
	.short	1998
	.short	1859
	.short	1984
	.short	24
	.short	201
	.short	200
	.short	72
	.short	65535
	.short	472
	.short	457
	.short	392
	.short	328
	.short	65535
	.short	536
	.short	585
	.short	520
	.short	712
	.short	65535
	.short	984
	.short	969
	.short	776
	.short	968
	.short	65535
	.short	1176
	.short	1033
	.short	1160
	.short	1096
	.short	65535
	.short	1304
	.short	1289
	.short	1288
	.short	1352
	.short	65535
	.short	1560
	.short	1673
	.short	1608
	.short	1544
	.short	65535
	.short	1944
	.short	1865
	.short	1864
	.short	1928
	.short	65535
	.short	216
	.short	9
	.short	136
	.short	8
	.short	65535
	.short	408
	.short	329
	.short	456
	.short	264
	.short	65535
	.short	728
	.short	521
	.short	584
	.short	648
	.short	65535
	.short	856
	.short	841
	.short	840
	.short	904
	.short	65535
	.short	1240
	.short	1097
	.short	1032
	.short	1224
	.short	65535
	.short	1496
	.short	1481
	.short	1480
	.short	1416
	.short	65535
	.short	1752
	.short	1609
	.short	1736
	.short	1672
	.short	65535
	.short	2008
	.short	1929
	.short	1800
	.short	1992
	.short	65535
	.short	86
	.short	85
	.short	139
	.short	133
	.short	65535
	.short	470
	.short	469
	.short	395
	.short	325
	.short	65535
	.short	598
	.short	725
	.short	715
	.short	709
	.short	65535
	.short	854
	.short	853
	.short	907
	.short	837
	.short	65535
	.short	1238
	.short	1173
	.short	1227
	.short	1157
	.short	65535
	.short	1302
	.short	1365
	.short	1291
	.short	1477
	.short	65535
	.short	1686
	.short	1621
	.short	1739
	.short	1541
	.short	65535
	.short	2006
	.short	1813
	.short	1803
	.short	1925
	.short	65535
	.short	150
	.short	21
	.short	203
	.short	197
	.short	65535
	.short	342
	.short	405
	.short	331
	.short	453
	.short	65535
	.short	534
	.short	661
	.short	651
	.short	581
	.short	65535
	.short	790
	.short	789
	.short	843
	.short	773
	.short	65535
	.short	1110
	.short	1045
	.short	1099
	.short	1093
	.short	65535
	.short	1494
	.short	1493
	.short	1419
	.short	1349
	.short	65535
	.short	1622
	.short	1685
	.short	1675
	.short	1605
	.short	65535
	.short	1814
	.short	2005
	.short	1995
	.short	1797
	.short	65535
	.short	220
	.short	206
	.short	73
	.short	7
	.short	65535
	.short	476
	.short	462
	.short	393
	.short	391
	.short	65535
	.short	732
	.short	718
	.short	713
	.short	647
	.short	65535
	.short	860
	.short	782
	.short	777
	.short	967
	.short	65535
	.short	1116
	.short	1102
	.short	1225
	.short	1031
	.short	65535
	.short	1436
	.short	1422
	.short	1353
	.short	1415
	.short	65535
	.short	1756
	.short	1742
	.short	1737
	.short	1735
	.short	65535
	.short	2012
	.short	1870
	.short	1993
	.short	1991
	.short	65535
	.short	156
	.short	14
	.short	137
	.short	135
	.short	65535
	.short	348
	.short	270
	.short	265
	.short	455
	.short	65535
	.short	604
	.short	654
	.short	649
	.short	711
	.short	65535
	.short	924
	.short	910
	.short	905
	.short	839
	.short	65535
	.short	1180
	.short	1166
	.short	1161
	.short	1095
	.short	65535
	.short	1372
	.short	1486
	.short	1417
	.short	1287
	.short	65535
	.short	1692
	.short	1614
	.short	1545
	.short	1543
	.short	65535
	.short	1820
	.short	1806
	.short	1801
	.short	1799
	.short	65535
	.short	151
	.short	147
	.short	10
	.short	71
	.short	65535
	.short	471
	.short	339
	.short	266
	.short	263
	.short	65535
	.short	599
	.short	723
	.short	522
	.short	519
	.short	65535
	.short	855
	.short	979
	.short	970
	.short	775
	.short	65535
	.short	1175
	.short	1043
	.short	1226
	.short	1223
	.short	65535
	.short	1303
	.short	1427
	.short	1354
	.short	1479
	.short	65535
	.short	1559
	.short	1683
	.short	1610
	.short	1671
	.short	65535
	.short	1943
	.short	1811
	.short	1930
	.short	1863
	.short	65535
	.short	87
	.short	83
	.short	74
	.short	199
	.short	65535
	.short	279
	.short	467
	.short	394
	.short	327
	.short	65535
	.short	535
	.short	659
	.short	586
	.short	583
	.short	65535
	.short	983
	.short	851
	.short	906
	.short	903
	.short	65535
	.short	1239
	.short	1107
	.short	1098
	.short	1159
	.short	65535
	.short	1431
	.short	1363
	.short	1418
	.short	1351
	.short	65535
	.short	1623
	.short	1619
	.short	1546
	.short	1607
	.short	65535
	.short	1815
	.short	1939
	.short	1802
	.short	1927
	.short	65535
	.short	26
	.short	217
	.short	17
	.short	65535
	.short	65535
	.short	282
	.short	409
	.short	337
	.short	65535
	.short	65535
	.short	666
	.short	537
	.short	529
	.short	65535
	.short	65535
	.short	986
	.short	793
	.short	849
	.short	65535
	.short	65535
	.short	1242
	.short	1113
	.short	1169
	.short	65535
	.short	65535
	.short	1498
	.short	1369
	.short	1489
	.short	65535
	.short	65535
	.short	1562
	.short	1561
	.short	1553
	.short	65535
	.short	65535
	.short	1818
	.short	2009
	.short	1873
	.short	65535
	.short	65535
	.short	218
	.short	153
	.short	209
	.short	65535
	.short	65535
	.short	346
	.short	345
	.short	465
	.short	65535
	.short	65535
	.short	602
	.short	601
	.short	657
	.short	65535
	.short	65535
	.short	858
	.short	921
	.short	913
	.short	65535
	.short	65535
	.short	1178
	.short	1049
	.short	1105
	.short	65535
	.short	65535
	.short	1370
	.short	1497
	.short	1297
	.short	65535
	.short	65535
	.short	1754
	.short	1625
	.short	1681
	.short	65535
	.short	65535
	.short	1946
	.short	1881
	.short	1809
	.short	65535
	.short	65535
	.short	32
	.short	157
	.short	77
	.short	0
	.short	131
	.short	224
	.short	285
	.short	269
	.short	322
	.short	259
	.short	352
	.short	669
	.short	589
	.short	706
	.short	643
	.short	416
	.short	861
	.short	781
	.short	898
	.short	899
	.short	608
	.short	1181
	.short	1037
	.short	1090
	.short	1218
	.short	672
	.short	1373
	.short	1357
	.short	1410
	.short	1346
	.short	800
	.short	1629
	.short	1613
	.short	1666
	.short	1730
	.short	928
	.short	1949
	.short	1869
	.short	1922
	.short	1986
	.short	96
	.short	221
	.short	205
	.short	130
	.short	3
	.short	160
	.short	349
	.short	461
	.short	450
	.short	451
	.short	288
	.short	605
	.short	717
	.short	705
	.short	577
	.short	480
	.short	989
	.short	909
	.short	962
	.short	963
	.short	544
	.short	1117
	.short	1165
	.short	1154
	.short	1219
	.short	736
	.short	1501
	.short	1485
	.short	1472
	.short	1411
	.short	864
	.short	1565
	.short	1741
	.short	1603
	.short	1537
	.short	992
	.short	2013
	.short	1933
	.short	1794
	.short	1795
	.size	_ZL7idx_tab, 2560

	.type	__hip_cuid_794236f6d9ab0dff,@object
